# attention PV segment: all 8 V-fragment LDS reads issued up front into freed score registers
# speedup vs baseline: 1.0084x; 1.0003x over previous
; DI void attn_unit(int tb_, char* shm, const bf16_t* Qp, const bf16_t* Kp, const bf16_t* Vtp, int nkeys, int nrows, bf16_t* Op) {
;     ...
;             const char* kb = Kl + bf * AT_KB + r32 * AT_KP + 16 * hi;
; #pragma unroll
;             for (int s = 0; s < 6; ++s) { const bf16x8 k0 = *(const bf16x8*)(kb + 32 * s); const bf16x8 k1 = *(const bf16x8*)(kb + 32 * AT_KP + 32 * s);
;                 pa0 = __builtin_amdgcn_mfma_f32_32x32x16_bf16(k0, qf0[s], pa0, 0, 0, 0); pa1 = __builtin_amdgcn_mfma_f32_32x32x16_bf16(k1, qf0[s], pa1, 0, 0, 0);
;                 pb0 = __builtin_amdgcn_mfma_f32_32x32x16_bf16(k0, qf1[s], pb0, 0, 0, 0); pb1 = __builtin_amdgcn_mfma_f32_32x32x16_bf16(k1, qf1[s], pb1, 0, 0, 0); }
;     ...
;             const char* vb = Vl + bf * AT_VB + r32 * AT_VP + 8 * hi;
; #pragma unroll
;             for (int kh = 0; kh < 2; ++kh) {
;                 u32x2 va0[2], va1[2], vc0[2], vc1[2];
; #pragma unroll
;                 for (int k2 = 0; k2 < 2; ++k2) { const int ks = 2 * kh + k2; va0[k2] = *(const u32x2*)(vb + 32 * ks); va1[k2] = *(const u32x2*)(vb + 32 * ks + 16); vc0[k2] = *(const u32x2*)(vb + 32 * AT_VP + 32 * ks); vc1[k2] = *(const u32x2*)(vb + 32 * AT_VP + 32 * ks + 16); }
; #pragma unroll
;                 for (int k2 = 0; k2 < 2; ++k2) { const int ks = 2 * kh + k2;
;                     const bf16x8 vfa = __builtin_bit_cast(bf16x8, ((u32x4){va0[k2].x, va0[k2].y, va1[k2].x, va1[k2].y})), vfc = __builtin_bit_cast(bf16x8, ((u32x4){vc0[k2].x, vc0[k2].y, vc1[k2].x, vc1[k2].y}));
;                     oa0 = __builtin_amdgcn_mfma_f32_32x32x16_bf16(qa[ks], vfa, oa0, 0, 0, 0); oa1 = __builtin_amdgcn_mfma_f32_32x32x16_bf16(qa[ks], vfc, oa1, 0, 0, 0);
;                     ob0 = __builtin_amdgcn_mfma_f32_32x32x16_bf16(qb4[ks], vfa, ob0, 0, 0, 0); ob1 = __builtin_amdgcn_mfma_f32_32x32x16_bf16(qb4[ks], vfc, ob1, 0, 0, 0); }
.Lat_val_skip:
	s_waitcnt lgkmcnt(0)
	s_barrier
	s_setprio 1
	s_and_b32 s37, s36, 1
	s_andn2_b64 vcc, exec, s[18:19]
	s_cbranch_vccnz .Lat_mm_skip
	s_mul_i32 s20, s37, 0x2200
	v_add_u32_e32 v229, s20, v204
	v_add_u32_e32 v228, 0x6800, v229
	v_add_u32_e32 v229, 0x7800, v229
	ds_read2_b64 v[80:83], v228 offset1:2
	ds_read2_b64 v[84:87], v229 offset0:32 offset1:34
	ds_read2_b64 v[88:91], v228 offset0:4 offset1:6
	ds_read2_b64 v[92:95], v229 offset0:36 offset1:38
	ds_read2_b64 v[112:115], v228 offset0:8 offset1:10
	ds_read2_b64 v[116:119], v229 offset0:40 offset1:42
	ds_read2_b64 v[120:123], v228 offset0:12 offset1:14
	ds_read2_b64 v[124:127], v229 offset0:44 offset1:46
	s_waitcnt lgkmcnt(6)
	v_mfma_f32_32x32x16_bf16 v[32:47], v[100:103], v[80:83], v[32:47]
	v_mfma_f32_32x32x16_bf16 v[48:63], v[100:103], v[84:87], v[48:63]
	v_mfma_f32_32x32x16_bf16 v[16:31], v[64:67], v[80:83], v[16:31]
	v_mfma_f32_32x32x16_bf16 v[0:15], v[64:67], v[84:87], v[0:15]
	s_waitcnt lgkmcnt(4)
	v_mfma_f32_32x32x16_bf16 v[32:47], v[108:111], v[88:91], v[32:47]
	v_mfma_f32_32x32x16_bf16 v[48:63], v[108:111], v[92:95], v[48:63]
	v_mfma_f32_32x32x16_bf16 v[16:31], v[72:75], v[88:91], v[16:31]
	v_mfma_f32_32x32x16_bf16 v[0:15], v[72:75], v[92:95], v[0:15]
	s_waitcnt lgkmcnt(2)
	v_mfma_f32_32x32x16_bf16 v[32:47], v[104:107], v[112:115], v[32:47]
	v_mfma_f32_32x32x16_bf16 v[48:63], v[104:107], v[116:119], v[48:63]
	v_mfma_f32_32x32x16_bf16 v[16:31], v[68:71], v[112:115], v[16:31]
	v_mfma_f32_32x32x16_bf16 v[0:15], v[68:71], v[116:119], v[0:15]
	s_waitcnt lgkmcnt(0)
	v_mfma_f32_32x32x16_bf16 v[32:47], v[96:99], v[120:123], v[32:47]
	v_mfma_f32_32x32x16_bf16 v[48:63], v[96:99], v[124:127], v[48:63]
	v_mfma_f32_32x32x16_bf16 v[16:31], v[76:79], v[120:123], v[16:31]
	v_mfma_f32_32x32x16_bf16 v[0:15], v[76:79], v[124:127], v[0:15]
	s_cmp_lt_u32 s36, s35
	s_cbranch_scc0 .Lat_mm_skip
	s_xor_b32 s20, s37, 1
	s_mulk_i32 s20, 0x3400
	v_add_u32_e32 v92, s20, v210
	ds_read_b128 v[64:67], v92
	ds_read_b128 v[80:83], v92 offset:32
	ds_read_b128 v[84:87], v92 offset:6656
	ds_read_b128 v[216:219], v92 offset:6688
	s_waitcnt lgkmcnt(3)
	v_mfma_f32_32x32x16_bf16 v[96:111], v[64:67], v[172:175], 0
	v_mfma_f32_32x32x16_bf16 v[64:79], v[64:67], v[148:151], 0
	s_waitcnt lgkmcnt(2)
	v_mfma_f32_32x32x16_bf16 v[96:111], v[80:83], v[168:171], v[96:111]
	v_mfma_f32_32x32x16_bf16 v[64:79], v[80:83], v[140:143], v[64:79]
	ds_read_b128 v[80:83], v92 offset:64
	ds_read_b128 v[88:91], v92 offset:96
	ds_read_b128 v[220:223], v92 offset:6720
	ds_read_b128 v[224:227], v92 offset:6752
	s_waitcnt lgkmcnt(3)
	v_mfma_f32_32x32x16_bf16 v[96:111], v[80:83], v[164:167], v[96:111]
	v_mfma_f32_32x32x16_bf16 v[64:79], v[80:83], v[144:147], v[64:79]
	s_waitcnt lgkmcnt(2)
	v_mfma_f32_32x32x16_bf16 v[96:111], v[88:91], v[160:163], v[96:111]
	v_mfma_f32_32x32x16_bf16 v[64:79], v[88:91], v[136:139], v[64:79]
	ds_read_b128 v[80:83], v92 offset:128
	ds_read_b128 v[88:91], v92 offset:160
	ds_read_b128 v[242:245], v92 offset:6784
	ds_read_b128 v[246:249], v92 offset:6816
	v_mfma_f32_32x32x16_bf16 v[112:127], v[84:87], v[172:175], 0
	s_waitcnt lgkmcnt(3)
	v_mfma_f32_32x32x16_bf16 v[96:111], v[80:83], v[156:159], v[96:111]
	v_mfma_f32_32x32x16_bf16 v[64:79], v[80:83], v[132:135], v[64:79]
	v_mfma_f32_32x32x16_bf16 v[112:127], v[216:219], v[168:171], v[112:127]
	s_waitcnt lgkmcnt(2)
	v_mfma_f32_32x32x16_bf16 v[96:111], v[88:91], v[152:155], v[96:111]
	v_mfma_f32_32x32x16_bf16 v[64:79], v[88:91], v[128:131], v[64:79]
	v_mfma_f32_32x32x16_bf16 v[80:95], v[84:87], v[148:151], 0
	v_mfma_f32_32x32x16_bf16 v[112:127], v[220:223], v[164:167], v[112:127]
	v_mfma_f32_32x32x16_bf16 v[80:95], v[216:219], v[140:143], v[80:95]
	v_mfma_f32_32x32x16_bf16 v[112:127], v[224:227], v[160:163], v[112:127]
	v_mfma_f32_32x32x16_bf16 v[80:95], v[220:223], v[144:147], v[80:95]
	s_waitcnt lgkmcnt(1)
	v_mfma_f32_32x32x16_bf16 v[112:127], v[242:245], v[156:159], v[112:127]
	v_mfma_f32_32x32x16_bf16 v[80:95], v[224:227], v[136:139], v[80:95]
	s_waitcnt lgkmcnt(0)
	v_mfma_f32_32x32x16_bf16 v[112:127], v[246:249], v[152:155], v[112:127]
	v_mfma_f32_32x32x16_bf16 v[80:95], v[242:245], v[132:135], v[80:95]
	v_mfma_f32_32x32x16_bf16 v[80:95], v[246:249], v[128:131], v[80:95]
